# plus QKV phase cache-conversion items: the 8 / 4 float4 loads of an item in flight together instead of load-wait-convert-store ladders
# speedup vs baseline: 1.0012x; 1.0004x over previous
.LBB0_658:
	s_cmpk_gt_i32 s24, 0xff
	s_mov_b64 s[30:31], -1
	s_cbranch_scc0 .LBB0_660
	s_add_i32 s30, s24, 0xffffff00
	s_lshr_b32 s90, s30, 3
	s_load_dwordx2 s[30:31], s[22:23], 0x28
	s_lshl_b64 s[46:47], s[90:91], 17
	v_mov_b32_e32 v2, v200
	v_mov_b32_e32 v1, v3
	s_waitcnt lgkmcnt(0)
	s_add_u32 s46, s30, s46
	s_addc_u32 s47, s31, s47
	s_lshl_b64 s[30:31], s[90:91], 16
	s_add_u32 s30, s35, s30
	v_lshlrev_b32_e32 v12, 4, v2
	s_addc_u32 s31, s36, s31
	s_and_b32 s45, s37, 0x1c0
	v_bfe_u32 v6, v2, 4, 4
	v_and_b32_e32 v0, 0xf0, v12
	v_lshl_add_u64 v[8:9], s[46:47], 0, v[0:1]
	v_or_b32_e32 v1, s45, v6
	v_lshlrev_b32_e32 v10, 8, v1
	v_mov_b32_e32 v11, v3
	v_lshl_add_u64 v[4:5], v[8:9], 0, v[10:11]
	v_mul_u32_u24_e32 v1, 0x104, v6
	global_load_dwordx4 v[4:7], v[4:5], off
	v_or_b32_e32 v68, 0x1000, v10
	v_mov_b32_e32 v69, v3
	v_lshl_add_u64 v[68:69], v[8:9], 0, v[68:69]
	global_load_dwordx4 v[68:71], v[68:69], off
	v_or_b32_e32 v72, 0x2000, v10
	v_mov_b32_e32 v73, v3
	v_lshl_add_u64 v[72:73], v[8:9], 0, v[72:73]
	global_load_dwordx4 v[72:75], v[72:73], off
	v_or_b32_e32 v76, 0x3000, v10
	v_mov_b32_e32 v77, v3
	v_lshl_add_u64 v[76:77], v[8:9], 0, v[76:77]
	global_load_dwordx4 v[76:79], v[76:77], off
	v_add3_u32 v11, s34, v1, v0
	v_or_b32_e32 v0, 0x1000, v10
	v_mov_b32_e32 v1, v3
	v_lshl_add_u64 v[0:1], v[8:9], 0, v[0:1]
	v_add_u32_e32 v13, 0x1040, v11
	v_and_b32_e32 v18, 48, v12
	s_lshl_b32 s90, s45, 1
	s_waitcnt vmcnt(0)
	ds_write2_b32 v11, v4, v5 offset1:1
	ds_write2_b32 v11, v6, v7 offset0:2 offset1:3
	v_add_u32_e32 v0, 0x1048, v11
	v_mov_b32_e32 v1, v3
	s_waitcnt vmcnt(0)
	ds_write2_b32 v0, v70, v71 offset1:1
	v_or_b32_e32 v0, 0x2000, v10
	v_lshl_add_u64 v[0:1], v[8:9], 0, v[0:1]
	ds_write2_b32 v13, v68, v69 offset1:1
	v_add_u32_e32 v0, 0x2088, v11
	v_mov_b32_e32 v1, v3
	v_add_u32_e32 v13, 0x2080, v11
	s_waitcnt vmcnt(0)
	ds_write2_b32 v0, v74, v75 offset1:1
	v_or_b32_e32 v0, 0x3000, v10
	v_lshl_add_u64 v[0:1], v[8:9], 0, v[0:1]
	ds_write2_b32 v13, v72, v73 offset1:1
	v_add_u32_e32 v0, 0x30c8, v11
	v_add_u32_e32 v8, 0x30c0, v11
	s_waitcnt vmcnt(0)
	ds_write2_b32 v0, v78, v79 offset1:1
	v_mul_u32_u24_e32 v0, 0x41, v18
	ds_write2_b32 v8, v76, v77 offset1:1
	v_lshlrev_b32_e32 v4, 2, v0
	v_and_b32_e32 v5, 0xfc, v2
	v_add3_u32 v6, s34, v4, v5
	v_add3_u32 v7, s34, v5, v4
	s_waitcnt lgkmcnt(0)
	s_barrier
	ds_read2_b32 v[0:1], v6 offset1:65
	v_add_u32_e32 v8, 0x800, v7
	ds_read2_b32 v[12:13], v8 offset0:8 offset1:73
	ds_read2_b32 v[4:5], v6 offset0:130 offset1:195
	ds_read2_b32 v[8:9], v8 offset0:138 offset1:203
	v_add_u32_e32 v6, 0x400, v6
	ds_read2_b32 v[10:11], v6 offset0:4 offset1:69
	v_add_u32_e32 v16, 0xc00, v7
	ds_read2_b32 v[14:15], v16 offset0:12 offset1:77
	ds_read2_b32 v[6:7], v6 offset0:134 offset1:199
	ds_read2_b32 v[16:17], v16 offset0:142 offset1:207
	s_waitcnt lgkmcnt(5)
	v_cvt_pk_f16_f32 v5, v4, v5
	v_cvt_pk_f16_f32 v4, v0, v1
	v_lshlrev_b32_e32 v0, 8, v2
	v_and_b32_e32 v0, 0xfc00, v0
	v_mov_b32_e32 v1, v3
	v_lshl_add_u64 v[0:1], s[30:31], 0, v[0:1]
	s_waitcnt lgkmcnt(4)
	v_cvt_pk_f16_f32 v9, v8, v9
	v_cvt_pk_f16_f32 v8, v12, v13
	v_lshl_add_u64 v[0:1], v[0:1], 0, s[90:91]
	v_lshlrev_b32_e32 v12, 1, v18
	v_mov_b32_e32 v13, v3
	s_waitcnt lgkmcnt(1)
	v_cvt_pk_f16_f32 v7, v6, v7
	v_cvt_pk_f16_f32 v6, v10, v11
	v_lshl_add_u64 v[0:1], v[0:1], 0, v[12:13]
	s_waitcnt lgkmcnt(0)
	v_cvt_pk_f16_f32 v11, v16, v17
	v_cvt_pk_f16_f32 v10, v14, v15
	global_store_dwordx4 v[0:1], v[4:7], off
	global_store_dwordx4 v[0:1], v[8:11], off offset:16
	s_barrier
	s_mov_b64 s[30:31], 0
.LBB0_660:
	s_andn2_b64 vcc, exec, s[30:31]
	s_cbranch_vccnz .LBB0_657
	s_load_dwordx2 s[30:31], s[22:23], 0x20
	v_lshlrev_b32_e32 v0, 2, v200
	v_and_b32_e32 v0, 0x3fc, v0
	v_add_u32_e32 v0, s43, v0
	s_waitcnt lgkmcnt(0)
	v_add_u32_e32 v56, 0xffffe400, v0
	v_mov_b32_e32 v64, v56
	v_ashrrev_i32_e32 v65, 31, v56
	v_lshl_add_u64 v[64:65], v[64:65], 2, s[30:31]
	global_load_dwordx4 v[20:23], v[64:65], off
	v_add_u32_e32 v57, 0xffffe800, v0
	v_mov_b32_e32 v64, v57
	v_ashrrev_i32_e32 v65, 31, v57
	v_lshl_add_u64 v[64:65], v[64:65], 2, s[30:31]
	global_load_dwordx4 v[24:27], v[64:65], off
	v_add_u32_e32 v58, 0xffffec00, v0
	v_mov_b32_e32 v64, v58
	v_ashrrev_i32_e32 v65, 31, v58
	v_lshl_add_u64 v[64:65], v[64:65], 2, s[30:31]
	global_load_dwordx4 v[28:31], v[64:65], off
	v_add_u32_e32 v59, 0xfffff000, v0
	v_mov_b32_e32 v64, v59
	v_ashrrev_i32_e32 v65, 31, v59
	v_lshl_add_u64 v[64:65], v[64:65], 2, s[30:31]
	global_load_dwordx4 v[32:35], v[64:65], off
	v_add_u32_e32 v60, 0xfffff400, v0
	v_mov_b32_e32 v64, v60
	v_ashrrev_i32_e32 v65, 31, v60
	v_lshl_add_u64 v[64:65], v[64:65], 2, s[30:31]
	global_load_dwordx4 v[36:39], v[64:65], off
	v_add_u32_e32 v61, 0xfffff800, v0
	v_mov_b32_e32 v64, v61
	v_ashrrev_i32_e32 v65, 31, v61
	v_lshl_add_u64 v[64:65], v[64:65], 2, s[30:31]
	global_load_dwordx4 v[40:43], v[64:65], off
	v_add_u32_e32 v62, 0xfffffc00, v0
	v_mov_b32_e32 v64, v62
	v_ashrrev_i32_e32 v65, 31, v62
	v_lshl_add_u64 v[64:65], v[64:65], 2, s[30:31]
	global_load_dwordx4 v[44:47], v[64:65], off
	v_mov_b32_e32 v63, v0
	v_mov_b32_e32 v64, v63
	v_ashrrev_i32_e32 v65, 31, v63
	v_lshl_add_u64 v[64:65], v[64:65], 2, s[30:31]
	global_load_dwordx4 v[52:55], v[64:65], off
	v_mov_b32_e32 v64, v56
	v_ashrrev_i32_e32 v65, 31, v56
	v_lshl_add_u64 v[0:1], v[64:65], 1, s[28:29]
	s_waitcnt vmcnt(7)
	v_cvt_f16_f32_e32 v2, v20
	v_cvt_pk_f16_f32 v21, v21, v22
	v_pack_b32_f16 v20, v2, v21
	v_cvt_f16_f32_e32 v2, v23
	v_alignbit_b32 v21, v2, v21, 16
	global_store_dwordx2 v[0:1], v[20:21], off
	v_mov_b32_e32 v64, v57
	v_ashrrev_i32_e32 v65, 31, v57
	v_lshl_add_u64 v[0:1], v[64:65], 1, s[28:29]
	s_waitcnt vmcnt(7)
	v_cvt_f16_f32_e32 v2, v24
	v_cvt_pk_f16_f32 v25, v25, v26
	v_pack_b32_f16 v24, v2, v25
	v_cvt_f16_f32_e32 v2, v27
	v_alignbit_b32 v25, v2, v25, 16
	global_store_dwordx2 v[0:1], v[24:25], off
	v_mov_b32_e32 v64, v58
	v_ashrrev_i32_e32 v65, 31, v58
	v_lshl_add_u64 v[0:1], v[64:65], 1, s[28:29]
	s_waitcnt vmcnt(7)
	v_cvt_f16_f32_e32 v2, v28
	v_cvt_pk_f16_f32 v29, v29, v30
	v_pack_b32_f16 v28, v2, v29
	v_cvt_f16_f32_e32 v2, v31
	v_alignbit_b32 v29, v2, v29, 16
	global_store_dwordx2 v[0:1], v[28:29], off
	v_mov_b32_e32 v64, v59
	v_ashrrev_i32_e32 v65, 31, v59
	v_lshl_add_u64 v[0:1], v[64:65], 1, s[28:29]
	s_waitcnt vmcnt(7)
	v_cvt_f16_f32_e32 v2, v32
	v_cvt_pk_f16_f32 v33, v33, v34
	v_pack_b32_f16 v32, v2, v33
	v_cvt_f16_f32_e32 v2, v35
	v_alignbit_b32 v33, v2, v33, 16
	global_store_dwordx2 v[0:1], v[32:33], off
	v_mov_b32_e32 v64, v60
	v_ashrrev_i32_e32 v65, 31, v60
	v_lshl_add_u64 v[0:1], v[64:65], 1, s[28:29]
	s_waitcnt vmcnt(7)
	v_cvt_f16_f32_e32 v2, v36
	v_cvt_pk_f16_f32 v37, v37, v38
	v_pack_b32_f16 v36, v2, v37
	v_cvt_f16_f32_e32 v2, v39
	v_alignbit_b32 v37, v2, v37, 16
	global_store_dwordx2 v[0:1], v[36:37], off
	v_mov_b32_e32 v64, v61
	v_ashrrev_i32_e32 v65, 31, v61
	v_lshl_add_u64 v[0:1], v[64:65], 1, s[28:29]
	s_waitcnt vmcnt(7)
	v_cvt_f16_f32_e32 v2, v40
	v_cvt_pk_f16_f32 v41, v41, v42
	v_pack_b32_f16 v40, v2, v41
	v_cvt_f16_f32_e32 v2, v43
	v_alignbit_b32 v41, v2, v41, 16
	global_store_dwordx2 v[0:1], v[40:41], off
	v_mov_b32_e32 v64, v62
	v_ashrrev_i32_e32 v65, 31, v62
	v_lshl_add_u64 v[0:1], v[64:65], 1, s[28:29]
	s_waitcnt vmcnt(7)
	v_cvt_f16_f32_e32 v2, v44
	v_cvt_pk_f16_f32 v45, v45, v46
	v_pack_b32_f16 v44, v2, v45
	v_cvt_f16_f32_e32 v2, v47
	v_alignbit_b32 v45, v2, v45, 16
	global_store_dwordx2 v[0:1], v[44:45], off
	v_mov_b32_e32 v64, v63
	v_ashrrev_i32_e32 v65, 31, v63
	v_lshl_add_u64 v[0:1], v[64:65], 1, s[28:29]
	s_waitcnt vmcnt(7)
	v_cvt_f16_f32_e32 v2, v52
	v_cvt_pk_f16_f32 v53, v53, v54
	v_pack_b32_f16 v52, v2, v53
	v_cvt_f16_f32_e32 v2, v55
	v_alignbit_b32 v53, v2, v53, 16
	global_store_dwordx2 v[0:1], v[52:53], off
	s_branch .LBB0_657
